# ph11 (conv fix-up of block-boundary rows) hand-written: all 24 loads of an item in flight, one wait
# speedup vs baseline: 1.0175x; 1.0175x over previous
.LBB0_238:
	s_andn2_b64 vcc, exec, s[10:11]
	s_cbranch_vccnz .LBB0_248
	s_cmp_eq_u32 s87, 11
	s_cbranch_scc0 .LBB0_248
	v_mov_b32_e32 v1, v163
	s_mov_b32 s2, s75
	s_nop 0
	v_lshl_add_u32 v1, s2, 9, v1
	s_mov_b32 s2, 0x58000
	v_cmp_gt_i32_e32 vcc, s2, v1
	s_and_saveexec_b64 s[10:11], vcc
	s_mov_b32 s20, 0xb000
	s_movk_i32 s21, 0x5000
	s_cbranch_execz .LBB0_247
	s_load_dwordx4 s[44:47], s[0:1], 0xf0
	s_add_u32 s12, s66, 0x30000000
	s_addc_u32 s13, s67, 0
	s_add_u32 s14, s66, 0x1a000000
	v_mov_b32_e32 v2, 0xb07
	s_addc_u32 s15, s67, 0
	v_lshl_add_u32 v138, v1, 3, v2
	s_lshl_b32 s2, s73, 3
	v_lshlrev_b32_e32 v139, 4, v1
	s_lshl_b32 s3, s73, 4
	s_mov_b64 s[16:17], 0
	s_mov_b64 s[18:19], 0
	s_mov_b32 s8, 0x2e8ba2e9
	s_mov_b32 s9, 0x5800
	s_movk_i32 s3, 0x2c00
	s_waitcnt lgkmcnt(0)
.Lfix_loop:
	v_mul_hi_u32 v2, v1, s8
	v_lshrrev_b32_e32 v2, 6, v2
	v_mul_u32_u24_e32 v3, 0x160, v2
	v_sub_u32_e32 v3, v1, v3
	v_lshlrev_b32_e32 v4, 3, v3
	v_lshrrev_b32_e32 v5, 7, v4
	v_and_b32_e32 v6, 0x7f, v4
	v_lshl_add_u32 v6, v5, 8, v6
	v_and_b32_e32 v7, 31, v2
	v_cmp_ne_u32_e32 vcc, 0, v7
	v_mul_lo_u32 v10, v2, s9
	v_add_u32_e32 v10, v10, v6
	v_cndmask_b32_e64 v16, 0, -1, vcc
	v_cndmask_b32_e64 v9, 0, 1, vcc
	v_sub_u32_e32 v8, v2, v9
	v_mul_lo_u32 v12, v8, s9
	v_add3_u32 v12, v12, v6, s3
	v_mov_b32_e32 v11, 0
	v_mov_b32_e32 v13, 0
	v_lshl_add_u64 v[10:11], v[10:11], 1, s[12:13]
	v_lshl_add_u64 v[12:13], v[12:13], 1, s[12:13]
	s_mov_b64 s[16:17], 0x2c00
	v_lshl_add_u64 v[14:15], v[10:11], 0, s[16:17]
	v_lshl_add_u64 v[18:19], v[12:13], 0, s[16:17]
	global_load_dwordx4 v[20:23], v[12:13], off
	global_load_dwordx4 v[24:27], v[12:13], off offset:256
	global_load_dwordx4 v[28:31], v[18:19], off
	global_load_dwordx4 v[32:35], v[18:19], off offset:256
	global_load_dwordx4 v[36:39], v[10:11], off
	global_load_dwordx4 v[40:43], v[10:11], off offset:256
	global_load_dwordx4 v[44:47], v[14:15], off
	global_load_dwordx4 v[48:51], v[14:15], off offset:256
	v_lshlrev_b32_e32 v10, 2, v4
	v_mov_b32_e32 v11, 0
	v_lshl_add_u64 v[12:13], s[44:45], 0, v[10:11]
	v_lshl_add_u64 v[14:15], s[46:47], 0, v[10:11]
	global_load_dwordx4 v[52:55], v[14:15], off offset:0
	global_load_dwordx4 v[56:59], v[14:15], off offset:16
	s_mov_b64 s[16:17], 0x2c00
	v_lshl_add_u64 v[18:19], v[14:15], 0, s[16:17]
	global_load_dwordx4 v[84:87], v[18:19], off
	global_load_dwordx4 v[88:91], v[18:19], off offset:16
	global_load_dwordx4 v[60:63], v[12:13], off offset:0
	global_load_dwordx4 v[64:67], v[12:13], off offset:16
	s_mov_b64 s[16:17], 0x2c00
	v_lshl_add_u64 v[18:19], v[12:13], 0, s[16:17]
	global_load_dwordx4 v[92:95], v[18:19], off
	global_load_dwordx4 v[96:99], v[18:19], off offset:16
	s_mov_b64 s[16:17], 0x5800
	v_lshl_add_u64 v[18:19], v[12:13], 0, s[16:17]
	global_load_dwordx4 v[68:71], v[18:19], off
	global_load_dwordx4 v[72:75], v[18:19], off offset:16
	s_mov_b64 s[16:17], 0x8400
	v_lshl_add_u64 v[18:19], v[12:13], 0, s[16:17]
	global_load_dwordx4 v[100:103], v[18:19], off
	global_load_dwordx4 v[104:107], v[18:19], off offset:16
	s_mov_b64 s[16:17], 0xb000
	v_lshl_add_u64 v[18:19], v[12:13], 0, s[16:17]
	global_load_dwordx4 v[76:79], v[18:19], off
	global_load_dwordx4 v[80:83], v[18:19], off offset:16
	s_mov_b64 s[16:17], 0xdc00
	v_lshl_add_u64 v[18:19], v[12:13], 0, s[16:17]
	global_load_dwordx4 v[108:111], v[18:19], off
	global_load_dwordx4 v[112:115], v[18:19], off offset:16
	v_mul_u32_u24_e32 v10, 0x58000, v2
	v_lshl_add_u32 v10, v4, 1, v10
	v_mov_b32_e32 v11, 0
	v_lshl_add_u64 v[10:11], s[14:15], 0, v[10:11]
	s_waitcnt vmcnt(0)
	v_and_b32_e32 v20, v20, v16
	v_and_b32_e32 v21, v21, v16
	v_and_b32_e32 v22, v22, v16
	v_and_b32_e32 v23, v23, v16
	v_and_b32_e32 v24, v24, v16
	v_and_b32_e32 v25, v25, v16
	v_and_b32_e32 v26, v26, v16
	v_and_b32_e32 v27, v27, v16
	v_and_b32_e32 v28, v28, v16
	v_and_b32_e32 v29, v29, v16
	v_and_b32_e32 v30, v30, v16
	v_and_b32_e32 v31, v31, v16
	v_and_b32_e32 v32, v32, v16
	v_and_b32_e32 v33, v33, v16
	v_and_b32_e32 v34, v34, v16
	v_and_b32_e32 v35, v35, v16
	v_lshlrev_b32_e32 v116, 16, v20
	v_and_b32_e32 v117, 0xffff0000, v20
	v_lshlrev_b32_e32 v118, 16, v21
	v_and_b32_e32 v119, 0xffff0000, v21
	v_lshlrev_b32_e32 v120, 16, v22
	v_and_b32_e32 v121, 0xffff0000, v22
	v_lshlrev_b32_e32 v122, 16, v23
	v_and_b32_e32 v123, 0xffff0000, v23
	v_lshlrev_b32_e32 v180, 16, v24
	v_and_b32_e32 v181, 0xffff0000, v24
	v_lshlrev_b32_e32 v182, 16, v25
	v_and_b32_e32 v183, 0xffff0000, v25
	v_lshlrev_b32_e32 v184, 16, v26
	v_and_b32_e32 v185, 0xffff0000, v26
	v_lshlrev_b32_e32 v186, 16, v27
	v_and_b32_e32 v187, 0xffff0000, v27
	v_lshlrev_b32_e32 v124, 16, v28
	v_and_b32_e32 v125, 0xffff0000, v28
	v_lshlrev_b32_e32 v126, 16, v29
	v_and_b32_e32 v127, 0xffff0000, v29
	v_lshlrev_b32_e32 v128, 16, v30
	v_and_b32_e32 v129, 0xffff0000, v30
	v_lshlrev_b32_e32 v130, 16, v31
	v_and_b32_e32 v131, 0xffff0000, v31
	v_lshlrev_b32_e32 v188, 16, v32
	v_and_b32_e32 v189, 0xffff0000, v32
	v_lshlrev_b32_e32 v190, 16, v33
	v_and_b32_e32 v191, 0xffff0000, v33
	v_lshlrev_b32_e32 v192, 16, v34
	v_and_b32_e32 v193, 0xffff0000, v34
	v_lshlrev_b32_e32 v194, 16, v35
	v_and_b32_e32 v195, 0xffff0000, v35
	v_lshlrev_b32_e32 v132, 16, v36
	v_and_b32_e32 v133, 0xffff0000, v36
	v_lshlrev_b32_e32 v134, 16, v37
	v_and_b32_e32 v135, 0xffff0000, v37
	v_lshlrev_b32_e32 v136, 16, v38
	v_and_b32_e32 v137, 0xffff0000, v38
	v_lshlrev_b32_e32 v138, 16, v39
	v_and_b32_e32 v139, 0xffff0000, v39
	v_lshlrev_b32_e32 v196, 16, v40
	v_and_b32_e32 v197, 0xffff0000, v40
	v_lshlrev_b32_e32 v198, 16, v41
	v_and_b32_e32 v199, 0xffff0000, v41
	v_lshlrev_b32_e32 v200, 16, v42
	v_and_b32_e32 v201, 0xffff0000, v42
	v_lshlrev_b32_e32 v202, 16, v43
	v_and_b32_e32 v203, 0xffff0000, v43
	v_lshlrev_b32_e32 v140, 16, v44
	v_and_b32_e32 v141, 0xffff0000, v44
	v_lshlrev_b32_e32 v142, 16, v45
	v_and_b32_e32 v143, 0xffff0000, v45
	v_lshlrev_b32_e32 v144, 16, v46
	v_and_b32_e32 v145, 0xffff0000, v46
	v_lshlrev_b32_e32 v146, 16, v47
	v_and_b32_e32 v147, 0xffff0000, v47
	v_lshlrev_b32_e32 v204, 16, v48
	v_and_b32_e32 v205, 0xffff0000, v48
	v_lshlrev_b32_e32 v206, 16, v49
	v_and_b32_e32 v207, 0xffff0000, v49
	v_lshlrev_b32_e32 v208, 16, v50
	v_and_b32_e32 v209, 0xffff0000, v50
	v_lshlrev_b32_e32 v210, 16, v51
	v_and_b32_e32 v211, 0xffff0000, v51
	v_fma_f32 v212, v60, v116, v52
	v_fma_f32 v220, v92, v180, v84
	v_fma_f32 v213, v61, v117, v53
	v_fma_f32 v221, v93, v181, v85
	v_fma_f32 v214, v62, v118, v54
	v_fma_f32 v222, v94, v182, v86
	v_fma_f32 v215, v63, v119, v55
	v_fma_f32 v223, v95, v183, v87
	v_fma_f32 v216, v64, v120, v56
	v_fma_f32 v224, v96, v184, v88
	v_fma_f32 v217, v65, v121, v57
	v_fma_f32 v225, v97, v185, v89
	v_fma_f32 v218, v66, v122, v58
	v_fma_f32 v226, v98, v186, v90
	v_fma_f32 v219, v67, v123, v59
	v_fma_f32 v227, v99, v187, v91
	v_fmac_f32_e32 v212, v68, v124
	v_fmac_f32_e32 v220, v100, v188
	v_fmac_f32_e32 v213, v69, v125
	v_fmac_f32_e32 v221, v101, v189
	v_fmac_f32_e32 v214, v70, v126
	v_fmac_f32_e32 v222, v102, v190
	v_fmac_f32_e32 v215, v71, v127
	v_fmac_f32_e32 v223, v103, v191
	v_fmac_f32_e32 v216, v72, v128
	v_fmac_f32_e32 v224, v104, v192
	v_fmac_f32_e32 v217, v73, v129
	v_fmac_f32_e32 v225, v105, v193
	v_fmac_f32_e32 v218, v74, v130
	v_fmac_f32_e32 v226, v106, v194
	v_fmac_f32_e32 v219, v75, v131
	v_fmac_f32_e32 v227, v107, v195
	v_fmac_f32_e32 v212, v76, v132
	v_fmac_f32_e32 v220, v108, v196
	v_fmac_f32_e32 v213, v77, v133
	v_fmac_f32_e32 v221, v109, v197
	v_fmac_f32_e32 v214, v78, v134
	v_fmac_f32_e32 v222, v110, v198
	v_fmac_f32_e32 v215, v79, v135
	v_fmac_f32_e32 v223, v111, v199
	v_fmac_f32_e32 v216, v80, v136
	v_fmac_f32_e32 v224, v112, v200
	v_fmac_f32_e32 v217, v81, v137
	v_fmac_f32_e32 v225, v113, v201
	v_fmac_f32_e32 v218, v82, v138
	v_fmac_f32_e32 v226, v114, v202
	v_fmac_f32_e32 v219, v83, v139
	v_fmac_f32_e32 v227, v115, v203
	v_mul_f32_e32 v148, 0xbfb8aa3b, v212
	v_mul_f32_e32 v149, 0xbfb8aa3b, v213
	v_mul_f32_e32 v150, 0xbfb8aa3b, v214
	v_mul_f32_e32 v151, 0xbfb8aa3b, v215
	v_mul_f32_e32 v152, 0xbfb8aa3b, v216
	v_mul_f32_e32 v153, 0xbfb8aa3b, v217
	v_mul_f32_e32 v154, 0xbfb8aa3b, v218
	v_mul_f32_e32 v155, 0xbfb8aa3b, v219
	v_exp_f32_e32 v148, v148
	v_exp_f32_e32 v149, v149
	v_exp_f32_e32 v150, v150
	v_exp_f32_e32 v151, v151
	v_exp_f32_e32 v152, v152
	v_exp_f32_e32 v153, v153
	v_exp_f32_e32 v154, v154
	v_exp_f32_e32 v155, v155
	v_add_f32_e32 v148, 1.0, v148
	v_add_f32_e32 v149, 1.0, v149
	v_add_f32_e32 v150, 1.0, v150
	v_add_f32_e32 v151, 1.0, v151
	v_add_f32_e32 v152, 1.0, v152
	v_add_f32_e32 v153, 1.0, v153
	v_add_f32_e32 v154, 1.0, v154
	v_add_f32_e32 v155, 1.0, v155
	v_rcp_f32_e32 v148, v148
	v_rcp_f32_e32 v149, v149
	v_rcp_f32_e32 v150, v150
	v_rcp_f32_e32 v151, v151
	v_rcp_f32_e32 v152, v152
	v_rcp_f32_e32 v153, v153
	v_rcp_f32_e32 v154, v154
	v_rcp_f32_e32 v155, v155
	v_mul_f32_e32 v148, v212, v148
	v_mul_f32_e32 v149, v213, v149
	v_mul_f32_e32 v150, v214, v150
	v_mul_f32_e32 v151, v215, v151
	v_mul_f32_e32 v152, v216, v152
	v_mul_f32_e32 v153, v217, v153
	v_mul_f32_e32 v154, v218, v154
	v_mul_f32_e32 v155, v219, v155
	v_mul_f32_e32 v148, v220, v148
	v_mul_f32_e32 v149, v221, v149
	v_mul_f32_e32 v150, v222, v150
	v_mul_f32_e32 v151, v223, v151
	v_mul_f32_e32 v152, v224, v152
	v_mul_f32_e32 v153, v225, v153
	v_mul_f32_e32 v154, v226, v154
	v_mul_f32_e32 v155, v227, v155
	v_cvt_pk_bf16_f32 v164, v148, v149
	v_cvt_pk_bf16_f32 v165, v150, v151
	v_cvt_pk_bf16_f32 v166, v152, v153
	v_cvt_pk_bf16_f32 v167, v154, v155
	global_store_dwordx4 v[10:11], v[164:167], off
	v_fma_f32 v212, v60, v124, v52
	v_fma_f32 v220, v92, v188, v84
	v_fma_f32 v213, v61, v125, v53
	v_fma_f32 v221, v93, v189, v85
	v_fma_f32 v214, v62, v126, v54
	v_fma_f32 v222, v94, v190, v86
	v_fma_f32 v215, v63, v127, v55
	v_fma_f32 v223, v95, v191, v87
	v_fma_f32 v216, v64, v128, v56
	v_fma_f32 v224, v96, v192, v88
	v_fma_f32 v217, v65, v129, v57
	v_fma_f32 v225, v97, v193, v89
	v_fma_f32 v218, v66, v130, v58
	v_fma_f32 v226, v98, v194, v90
	v_fma_f32 v219, v67, v131, v59
	v_fma_f32 v227, v99, v195, v91
	v_fmac_f32_e32 v212, v68, v132
	v_fmac_f32_e32 v220, v100, v196
	v_fmac_f32_e32 v213, v69, v133
	v_fmac_f32_e32 v221, v101, v197
	v_fmac_f32_e32 v214, v70, v134
	v_fmac_f32_e32 v222, v102, v198
	v_fmac_f32_e32 v215, v71, v135
	v_fmac_f32_e32 v223, v103, v199
	v_fmac_f32_e32 v216, v72, v136
	v_fmac_f32_e32 v224, v104, v200
	v_fmac_f32_e32 v217, v73, v137
	v_fmac_f32_e32 v225, v105, v201
	v_fmac_f32_e32 v218, v74, v138
	v_fmac_f32_e32 v226, v106, v202
	v_fmac_f32_e32 v219, v75, v139
	v_fmac_f32_e32 v227, v107, v203
	v_fmac_f32_e32 v212, v76, v140
	v_fmac_f32_e32 v220, v108, v204
	v_fmac_f32_e32 v213, v77, v141
	v_fmac_f32_e32 v221, v109, v205
	v_fmac_f32_e32 v214, v78, v142
	v_fmac_f32_e32 v222, v110, v206
	v_fmac_f32_e32 v215, v79, v143
	v_fmac_f32_e32 v223, v111, v207
	v_fmac_f32_e32 v216, v80, v144
	v_fmac_f32_e32 v224, v112, v208
	v_fmac_f32_e32 v217, v81, v145
	v_fmac_f32_e32 v225, v113, v209
	v_fmac_f32_e32 v218, v82, v146
	v_fmac_f32_e32 v226, v114, v210
	v_fmac_f32_e32 v219, v83, v147
	v_fmac_f32_e32 v227, v115, v211
	v_mul_f32_e32 v148, 0xbfb8aa3b, v212
	v_mul_f32_e32 v149, 0xbfb8aa3b, v213
	v_mul_f32_e32 v150, 0xbfb8aa3b, v214
	v_mul_f32_e32 v151, 0xbfb8aa3b, v215
	v_mul_f32_e32 v152, 0xbfb8aa3b, v216
	v_mul_f32_e32 v153, 0xbfb8aa3b, v217
	v_mul_f32_e32 v154, 0xbfb8aa3b, v218
	v_mul_f32_e32 v155, 0xbfb8aa3b, v219
	v_exp_f32_e32 v148, v148
	v_exp_f32_e32 v149, v149
	v_exp_f32_e32 v150, v150
	v_exp_f32_e32 v151, v151
	v_exp_f32_e32 v152, v152
	v_exp_f32_e32 v153, v153
	v_exp_f32_e32 v154, v154
	v_exp_f32_e32 v155, v155
	v_add_f32_e32 v148, 1.0, v148
	v_add_f32_e32 v149, 1.0, v149
	v_add_f32_e32 v150, 1.0, v150
	v_add_f32_e32 v151, 1.0, v151
	v_add_f32_e32 v152, 1.0, v152
	v_add_f32_e32 v153, 1.0, v153
	v_add_f32_e32 v154, 1.0, v154
	v_add_f32_e32 v155, 1.0, v155
	v_rcp_f32_e32 v148, v148
	v_rcp_f32_e32 v149, v149
	v_rcp_f32_e32 v150, v150
	v_rcp_f32_e32 v151, v151
	v_rcp_f32_e32 v152, v152
	v_rcp_f32_e32 v153, v153
	v_rcp_f32_e32 v154, v154
	v_rcp_f32_e32 v155, v155
	v_mul_f32_e32 v148, v212, v148
	v_mul_f32_e32 v149, v213, v149
	v_mul_f32_e32 v150, v214, v150
	v_mul_f32_e32 v151, v215, v151
	v_mul_f32_e32 v152, v216, v152
	v_mul_f32_e32 v153, v217, v153
	v_mul_f32_e32 v154, v218, v154
	v_mul_f32_e32 v155, v219, v155
	v_mul_f32_e32 v148, v220, v148
	v_mul_f32_e32 v149, v221, v149
	v_mul_f32_e32 v150, v222, v150
	v_mul_f32_e32 v151, v223, v151
	v_mul_f32_e32 v152, v224, v152
	v_mul_f32_e32 v153, v225, v153
	v_mul_f32_e32 v154, v226, v154
	v_mul_f32_e32 v155, v227, v155
	v_cvt_pk_bf16_f32 v168, v148, v149
	v_cvt_pk_bf16_f32 v169, v150, v151
	v_cvt_pk_bf16_f32 v170, v152, v153
	v_cvt_pk_bf16_f32 v171, v154, v155
	s_mov_b64 s[16:17], 0x1600
	v_lshl_add_u64 v[12:13], v[10:11], 0, s[16:17]
	global_store_dwordx4 v[12:13], v[168:171], off
	v_add_u32_e32 v1, s73, v1
	s_mov_b32 s2, 0x57fff
	v_cmp_lt_i32_e32 vcc, s2, v1
	s_or_b64 s[18:19], vcc, s[18:19]
	s_andn2_b64 exec, exec, s[18:19]
	s_cbranch_execnz .Lfix_loop
